# attention: compiler-inserted vmcnt(0) before the first QK MFMA of a step replaced by a counted wait that lets the V-piece LDS-DMA issued just before stay in flight (it is only needed at the PV barrier
# speedup vs baseline: 1.0073x; 1.0073x over previous
; #define LAS __attribute__((address_space(3)))
; #define MFMA16(a, b, c) __builtin_amdgcn_mfma_f32_16x16x32_bf16((a), (b), (c), 0, 0, 0)
; __device__ __forceinline__ int att_fk(int key) { return ((key >> 3) & 3) + 4 * ((key >> 1) & 1); }
; #define ATT_BAR() do { asm volatile("s_waitcnt lgkmcnt(0)" ::: "memory"); __builtin_amdgcn_s_barrier(); asm volatile("" ::: "memory"); } while (0)
; __device__ __forceinline__ void attn_phase(const bf16_t* Q, const bf16_t* Kb, const bf16_t* VTa, const float* rpb, bf16_t* Y, LAS unsigned char* lds, int bx, int G, int tid, int wave, int lane) {
;     ...
;             rl[tid] = (tid < 465) ? rpb[h * 465 + min(tid, 464)] : -1.0e30f;
;         }
;         bf16x8 qf0, qf1;
;         { const bf16_t* qp = Q + (size_t)(r0 * 64 + c) * 1024 + h * 64 + 8 * fq; qf0 = *(const bf16x8*)qp; qf1 = *(const bf16x8*)(qp + 32); }
;         asm volatile("s_waitcnt vmcnt(0)" ::: "memory");
;         ATT_BAR();
;         for (int n = 0; n < 8; ++n) {
;             const int r = r0 + n, rs = min(max(r - 4, 0), 120);
;             const bool has_next = n < 7; const int rsn = min(max(r + 1 - 4, 0), 120); const bool newrow = has_next && (rsn != rs);
;             asm volatile("s_waitcnt vmcnt(1)" ::: "memory");
;             ATT_BAR();
;             f32x4 s[4][2];
;             float mx = -3.0e38f;
; #pragma unroll
;             for (int ii = 0; ii < 4; ++ii) {
;                 const int i = 4 * hf + ii, dr = rs + i - r + 7;
;                 float bia[8];
; #pragma unroll
;                 for (int j = 0; j < 8; ++j) bia[j] = rl[((unsigned)(j - wlo) < (unsigned)wwd) ? dr * 31 + dci0 + j : 480];
; #pragma unroll
;                 for (int ta = 0; ta < 2; ++ta) {
;                     const int key = cs + 8 * (fr >> 2) + 4 * ta + (fr & 3), fk = att_fk(key);
;                     const LAS unsigned char* kp = KL + ((rs + i) & 7) * 8192 + key * 128;
;                     const bf16x8 kf0 = *(const LAS bf16x8*)(kp + ((fq ^ fk) << 4)), kf1 = *(const LAS bf16x8*)(kp + (((4 + fq) ^ fk) << 4));
;                     f32x4 a = {0.f, 0.f, 0.f, 0.f};
;                     a = MFMA16(kf0, qf0, a); a = MFMA16(kf1, qf1, a);
.LBB0_450:
	s_or_b64 exec, exec, s[56:57]
	v_lshl_or_b32 v2, s94, 6, v47
	v_ashrrev_i32_e32 v3, 31, v2
	v_lshlrev_b64 v[2:3], 11, v[2:3]
	v_lshl_add_u64 v[2:3], s[62:63], 0, v[2:3]
	s_lshl_b32 s22, s20, 1
	v_lshl_add_u64 v[2:3], v[2:3], 0, s[22:23]
	v_mov_b32_e32 v89, v1
	v_lshl_add_u64 v[2:3], v[2:3], 0, v[88:89]
	global_load_dwordx4 v[6:9], v[2:3], off
	s_nop 0
	global_load_dwordx4 v[2:5], v[2:3], off offset:64
	s_waitcnt vmcnt(0)
	ds_write_b32 v53, v10
	s_waitcnt vmcnt(0)
	v_add_u32_e32 v10, s20, v48
	s_waitcnt lgkmcnt(0)
	s_barrier
	v_ashrrev_i32_e32 v11, 31, v10
	s_lshl_b32 s20, s93, 6
	v_lshlrev_b64 v[10:11], 14, v[10:11]
	s_and_b32 s20, s20, 0xfffffe00
	v_lshl_add_u64 v[92:93], v[44:45], 0, s[22:23]
	v_lshl_add_u64 v[94:95], v[66:67], 0, s[22:23]
	v_lshl_add_u64 v[96:97], v[68:69], 0, v[10:11]
	v_or_b32_e32 v98, s20, v47
	s_sub_i32 s95, s91, s94
	s_sub_i32 s20, s85, s94
	s_mov_b32 s30, 7
	s_mov_b32 s32, 0
.LBB0_451:
	s_max_i32 s31, s94, 4
	s_add_i32 s31, s31, -4
	s_max_i32 s56, s94, 3
	s_min_u32 s64, s31, 0x78
	s_add_i32 s56, s56, -3
	s_add_i32 s58, s95, s64
	s_add_i32 s59, s20, s64
	s_min_u32 s80, s56, 0x78
	s_cmp_lg_u32 s80, s64
	s_cselect_b64 s[56:57], -1, 0
	s_add_i32 s59, s30, s59
	s_add_i32 s60, s64, s85
	s_mul_i32 s61, s59, 31
	s_add_i32 s74, s61, 0xffffff27
	s_lshl_b32 s59, s60, 13
	s_and_b32 s75, s59, 0xe000
	v_add_u32_e32 v10, s74, v46
	s_waitcnt vmcnt(1)
	v_lshl_add_u32 v190, v10, 2, s84
	v_cndmask_b32_e64 v11, v194, v190, s[40:41]
	v_add_u32_e32 v14, s75, v61
	s_waitcnt lgkmcnt(0)
	s_barrier
	v_add_u32_e32 v19, v14, v55
	ds_read_b32 v202, v11
	v_add_u32_e32 v18, v14, v41
	ds_read_b128 v[14:17], v19
	v_cndmask_b32_e64 v11, v195, v190, s[42:43]
	ds_read_b32 v203, v11 offset:4
	v_cndmask_b32_e64 v11, v196, v190, s[44:45]
	ds_read_b32 v204, v11 offset:8
	v_cndmask_b32_e64 v11, v197, v190, s[46:47]
	ds_read_b32 v205, v11 offset:12
	v_cndmask_b32_e64 v11, v198, v190, s[48:49]
	ds_read_b32 v206, v11 offset:16
	v_cndmask_b32_e64 v11, v199, v190, s[50:51]
	ds_read_b32 v207, v11 offset:20
	v_cndmask_b32_e64 v11, v200, v190, s[52:53]
	v_cndmask_b32_e64 v10, v201, v190, s[54:55]
	ds_read_b32 v208, v11 offset:24
	ds_read_b32 v209, v10 offset:28
	ds_read_b128 v[10:13], v18
	s_waitcnt lgkmcnt(0)
	s_cmp_lg_u32 s32, 0
	s_cbranch_scc1 .Latt_vp0_pend
	s_waitcnt vmcnt(0)
	s_branch .Latt_vp0_done
.Latt_vp0_pend:
	s_waitcnt vmcnt(1)
; #define LAS __attribute__((address_space(3)))
; #define MFMA16(a, b, c) __builtin_amdgcn_mfma_f32_16x16x32_bf16((a), (b), (c), 0, 0, 0)
; #define SCHED_FENCE() __builtin_amdgcn_sched_barrier(0)
; __device__ __forceinline__ int att_fk(int key) { return ((key >> 3) & 3) + 4 * ((key >> 1) & 1); }
; #define ATT_K_PIECE(h_, row_, kg_) do { const int key = (kg_) * 8 + lr; \
;         __builtin_amdgcn_global_load_lds((const __attribute__((address_space(1))) unsigned*)(Kb + ((size_t)(row_) * 64 + key) * 1024 + (h_) * 64 + 8 * (lc ^ att_fk(key))), (LAS unsigned*)(KL + ((row_) & 7) * 8192 + (kg_) * 1024), 16, 0, 0); } while (0)
; #define ATT_BAR() do { asm volatile("s_waitcnt lgkmcnt(0)" ::: "memory"); __builtin_amdgcn_s_barrier(); asm volatile("" ::: "memory"); } while (0)
; __device__ __forceinline__ void attn_phase(const bf16_t* Q, const bf16_t* Kb, const bf16_t* VTa, const float* rpb, bf16_t* Y, LAS unsigned char* lds, int bx, int G, int tid, int wave, int lane) {
;     ...
; #pragma unroll
;             for (int ii = 0; ii < 4; ++ii) {
;                 const int i = 4 * hf + ii, dr = rs + i - r + 7;
;                 float bia[8];
; #pragma unroll
;                 for (int j = 0; j < 8; ++j) bia[j] = rl[((unsigned)(j - wlo) < (unsigned)wwd) ? dr * 31 + dci0 + j : 480];
; #pragma unroll
;                 for (int ta = 0; ta < 2; ++ta) {
;                     const int key = cs + 8 * (fr >> 2) + 4 * ta + (fr & 3), fk = att_fk(key);
;                     const LAS unsigned char* kp = KL + ((rs + i) & 7) * 8192 + key * 128;
;                     const bf16x8 kf0 = *(const LAS bf16x8*)(kp + ((fq ^ fk) << 4)), kf1 = *(const LAS bf16x8*)(kp + (((4 + fq) ^ fk) << 4));
;                     f32x4 a = {0.f, 0.f, 0.f, 0.f};
;                     a = MFMA16(kf0, qf0, a); a = MFMA16(kf1, qf1, a);
; #pragma unroll
;                     for (int idx = 0; idx < 4; ++idx) { a[idx] += bia[4 * ta + idx]; mx = fmaxf(mx, a[idx]); }
;                     s[ii][ta] = a;
;                 }
;             }
;             ATT_BAR();
;             SCHED_FENCE();
;             if (newrow) ATT_K_PIECE(h, rs + 8, wave);
.Latt_vp0_done:
	v_mfma_f32_16x16x32_bf16 v[10:13], v[10:13], v[6:9], 0
	s_add_i32 s59, s64, s89
	s_add_i32 vcc_hi, s61, 0xffffff46
	s_lshl_b32 s59, s59, 13
	v_mfma_f32_16x16x32_bf16 v[10:13], v[14:17], v[2:5], v[10:13]
	ds_read_b128 v[14:17], v18 offset:512
	ds_read_b128 v[18:21], v19 offset:512
	s_and_b32 vcc_lo, s59, 0xe000
	v_add_u32_e32 v22, vcc_lo, v61
	s_waitcnt lgkmcnt(1)
	v_mfma_f32_16x16x32_bf16 v[14:17], v[14:17], v[6:9], 0
	v_add_u32_e32 v27, v22, v55
	v_add_u32_e32 v26, v22, v41
	ds_read_b128 v[22:25], v27
	s_waitcnt lgkmcnt(1)
	v_mfma_f32_16x16x32_bf16 v[14:17], v[18:21], v[2:5], v[14:17]
	v_add_u32_e32 v18, vcc_hi, v46
	v_lshl_add_u32 v191, v18, 2, s84
	v_cndmask_b32_e64 v19, v194, v191, s[40:41]
	ds_read_b32 v210, v19
	v_cndmask_b32_e64 v19, v195, v191, s[42:43]
	ds_read_b32 v211, v19 offset:4
	v_cndmask_b32_e64 v19, v196, v191, s[44:45]
	ds_read_b32 v212, v19 offset:8
	v_cndmask_b32_e64 v19, v197, v191, s[46:47]
	ds_read_b32 v213, v19 offset:12
	v_cndmask_b32_e64 v19, v198, v191, s[48:49]
	ds_read_b32 v214, v19 offset:16
	v_cndmask_b32_e64 v19, v199, v191, s[50:51]
	ds_read_b32 v215, v19 offset:20
	v_cndmask_b32_e64 v19, v200, v191, s[52:53]
	v_cndmask_b32_e64 v18, v201, v191, s[54:55]
	ds_read_b32 v216, v19 offset:24
	ds_read_b32 v217, v18 offset:28
	ds_read_b128 v[18:21], v26
	s_waitcnt lgkmcnt(0)
	v_mfma_f32_16x16x32_bf16 v[18:21], v[18:21], v[6:9], 0
	s_add_i32 s59, s64, s90
	s_addk_i32 s61, 0xff65
	s_lshl_b32 s59, s59, 13
	v_mfma_f32_16x16x32_bf16 v[18:21], v[22:25], v[2:5], v[18:21]
	ds_read_b128 v[22:25], v26 offset:512
	ds_read_b128 v[26:29], v27 offset:512
	s_and_b32 s60, s59, 0xe000
	v_add_u32_e32 v30, s60, v61
	s_waitcnt lgkmcnt(1)
	v_mfma_f32_16x16x32_bf16 v[22:25], v[22:25], v[6:9], 0
	v_add_u32_e32 v35, v30, v55
	v_add_u32_e32 v34, v30, v41
	ds_read_b128 v[30:33], v35
	s_waitcnt lgkmcnt(1)
	v_mfma_f32_16x16x32_bf16 v[22:25], v[26:29], v[2:5], v[22:25]
	v_add_u32_e32 v26, s61, v46
	v_lshl_add_u32 v192, v26, 2, s84
	v_cndmask_b32_e64 v27, v194, v192, s[40:41]
	ds_read_b32 v102, v27
	v_cndmask_b32_e64 v27, v195, v192, s[42:43]
	ds_read_b32 v103, v27 offset:4
	v_cndmask_b32_e64 v27, v196, v192, s[44:45]
	ds_read_b32 v104, v27 offset:8
	v_cndmask_b32_e64 v27, v197, v192, s[46:47]
	ds_read_b32 v105, v27 offset:12
	v_cndmask_b32_e64 v27, v198, v192, s[48:49]
	ds_read_b32 v106, v27 offset:16
	v_cndmask_b32_e64 v27, v199, v192, s[50:51]
	ds_read_b32 v107, v27 offset:20
	v_cndmask_b32_e64 v27, v200, v192, s[52:53]
	v_cndmask_b32_e64 v26, v201, v192, s[54:55]
	ds_read_b32 v108, v27 offset:24
	ds_read_b32 v109, v26 offset:28
	ds_read_b128 v[26:29], v34
	s_waitcnt lgkmcnt(0)
	v_mfma_f32_16x16x32_bf16 v[26:29], v[26:29], v[6:9], 0
	s_add_i32 s58, s30, s58
	s_add_i32 s31, s64, s91
	s_mul_i32 s59, s58, 31
	v_mfma_f32_16x16x32_bf16 v[26:29], v[30:33], v[2:5], v[26:29]
	ds_read_b128 v[30:33], v34 offset:512
	ds_read_b128 v[34:37], v35 offset:512
	s_addk_i32 s59, 0xff27
	s_lshl_b32 s31, s31, 13
	s_waitcnt lgkmcnt(1)
	v_mfma_f32_16x16x32_bf16 v[30:33], v[30:33], v[6:9], 0
	s_and_b32 s58, s31, 0xe000
	v_add_u32_e32 v118, s58, v61
	v_add_u32_e32 v123, v118, v55
	s_waitcnt lgkmcnt(0)
	v_mfma_f32_16x16x32_bf16 v[30:33], v[34:37], v[2:5], v[30:33]
	v_add_u32_e32 v34, s59, v46
	v_lshl_add_u32 v193, v34, 2, s84
	v_cndmask_b32_e64 v35, v194, v193, s[40:41]
	ds_read_b32 v110, v35
	v_add_u32_e32 v122, v118, v41
	ds_read_b128 v[118:121], v123
	v_cndmask_b32_e64 v35, v195, v193, s[42:43]
	ds_read_b32 v111, v35 offset:4
	v_cndmask_b32_e64 v35, v196, v193, s[44:45]
	ds_read_b32 v112, v35 offset:8
	v_cndmask_b32_e64 v35, v197, v193, s[46:47]
	ds_read_b32 v113, v35 offset:12
	v_cndmask_b32_e64 v35, v198, v193, s[48:49]
	ds_read_b32 v114, v35 offset:16
	v_cndmask_b32_e64 v35, v199, v193, s[50:51]
	ds_read_b32 v115, v35 offset:20
	v_cndmask_b32_e64 v35, v200, v193, s[52:53]
	v_cndmask_b32_e64 v34, v201, v193, s[54:55]
	ds_read_b32 v116, v35 offset:24
	ds_read_b32 v117, v34 offset:28
	ds_read_b128 v[34:37], v122
	s_waitcnt lgkmcnt(0)
	v_mfma_f32_16x16x32_bf16 v[34:37], v[34:37], v[6:9], 0
	s_cmp_eq_u32 s80, s64
	v_mfma_f32_16x16x32_bf16 v[34:37], v[118:121], v[2:5], v[34:37]
	ds_read_b128 v[118:121], v122 offset:512
	ds_read_b128 v[122:125], v123 offset:512
	s_waitcnt lgkmcnt(0)
	s_barrier
	s_waitcnt lgkmcnt(1)
	v_mfma_f32_16x16x32_bf16 v[6:9], v[118:121], v[6:9], 0
	s_waitcnt lgkmcnt(0)
	v_mfma_f32_16x16x32_bf16 v[2:5], v[122:125], v[2:5], v[6:9]
	s_cbranch_scc1 .LBB0_453
	s_lshl_b32 s31, s64, 17
	s_add_u32 s58, s21, s31
	s_addc_u32 s59, s83, 0
	s_nop 1
	v_lshl_add_u64 v[6:7], s[58:59], 0, v[50:51]
	v_lshl_add_u64 v[6:7], v[6:7], 0, s[22:23]
	s_lshl_b32 s31, s64, 13
	v_lshl_add_u64 v[6:7], v[6:7], 0, v[0:1]
	s_mov_b64 s[58:59], 0x100000
	s_and_b32 s31, s31, 0xe000
	v_lshl_add_u64 v[6:7], v[6:7], 0, s[58:59]
	s_add_i32 m0, s86, s31
	s_nop 0
	global_load_lds_dwordx4 v[6:7], off

; #define SCHED_FENCE() __builtin_amdgcn_sched_barrier(0)
; #define ATT_V_PIECE(h_, row_, dg_) do { const int dh = (dg_) * 8 + lr; \
;         __builtin_amdgcn_global_load_lds((const __attribute__((address_space(1))) unsigned*)(VTa + (size_t)((h_) * 64 + dh) * T + (size_t)(row_) * 64 + 8 * (lc ^ att_fv(dh))), (LAS unsigned*)(VL + ((row_) & 7) * 8192 + (dg_) * 1024), 16, 0, 0); } while (0)
; #define ATT_BAR() do { asm volatile("s_waitcnt lgkmcnt(0)" ::: "memory"); __builtin_amdgcn_s_barrier(); asm volatile("" ::: "memory"); } while (0)
; __device__ __forceinline__ void attn_phase(const bf16_t* Q, const bf16_t* Kb, const bf16_t* VTa, const float* rpb, bf16_t* Y, LAS unsigned char* lds, int bx, int G, int tid, int wave, int lane) {
;     ...
;             ATT_BAR();
;             SCHED_FENCE();
;             if (newrow) ATT_V_PIECE(h, rs + 8, wave);
;             SCHED_FENCE();
.LBB0_461:
	s_waitcnt lgkmcnt(0)
	s_barrier
	s_mov_b32 s32, 0
	s_and_b64 vcc, exec, s[60:61]
	s_cbranch_vccnz .LBB0_463
	s_lshl_b32 s31, s64, 13
	s_lshl_b32 s60, s64, 7
	s_mov_b32 s61, s23
	s_and_b32 s31, s31, 0xe000
	v_lshl_add_u64 v[10:11], v[96:97], 0, s[60:61]
	s_mov_b64 s[60:61], 0x400
	s_add_i32 m0, s88, s31
	v_lshl_add_u64 v[10:11], v[10:11], 0, s[60:61]
	global_load_lds_dwordx4 v[10:11], off
	s_mov_b32 s32, 1

; #define LAS __attribute__((address_space(3)))
; #define MFMA16(a, b, c) __builtin_amdgcn_mfma_f32_16x16x32_bf16((a), (b), (c), 0, 0, 0)
; __device__ __forceinline__ int att_fk(int key) { return ((key >> 3) & 3) + 4 * ((key >> 1) & 1); }
; #define ATT_BAR() do { asm volatile("s_waitcnt lgkmcnt(0)" ::: "memory"); __builtin_amdgcn_s_barrier(); asm volatile("" ::: "memory"); } while (0)
; __device__ __forceinline__ void attn_phase(const bf16_t* Q, const bf16_t* Kb, const bf16_t* VTa, const float* rpb, bf16_t* Y, LAS unsigned char* lds, int bx, int G, int tid, int wave, int lane) {
;     ...
;             const int r = r0 + n, rs = min(max(r - 4, 0), 120);
;             const bool has_next = n < 7; const int rsn = min(max(r + 1 - 4, 0), 120); const bool newrow = has_next && (rsn != rs);
;             asm volatile("s_waitcnt vmcnt(1)" ::: "memory");
;             ATT_BAR();
;             f32x4 s[4][2];
;             float mx = -3.0e38f;
; #pragma unroll
;             for (int ii = 0; ii < 4; ++ii) {
;                 const int i = 4 * hf + ii, dr = rs + i - r + 7;
;                 float bia[8];
; #pragma unroll
;                 for (int j = 0; j < 8; ++j) bia[j] = rl[((unsigned)(j - wlo) < (unsigned)wwd) ? dr * 31 + dci0 + j : 480];
; #pragma unroll
;                 for (int ta = 0; ta < 2; ++ta) {
;                     const int key = cs + 8 * (fr >> 2) + 4 * ta + (fr & 3), fk = att_fk(key);
;                     const LAS unsigned char* kp = KL + ((rs + i) & 7) * 8192 + key * 128;
;                     const bf16x8 kf0 = *(const LAS bf16x8*)(kp + ((fq ^ fk) << 4)), kf1 = *(const LAS bf16x8*)(kp + (((4 + fq) ^ fk) << 4));
;                     f32x4 a = {0.f, 0.f, 0.f, 0.f};
;                     a = MFMA16(kf0, qf0, a); a = MFMA16(kf1, qf1, a);
.LBB0_465:
	s_or_b32 s20, s93, 7
	s_max_i32 s30, s20, 4
	s_add_i32 s30, s30, -4
	s_min_u32 s30, s30, 0x78
	s_add_i32 s31, s30, s85
	s_sub_i32 s60, s31, s20
	s_lshl_b32 s31, s31, 13
	v_mad_u64_u32 v[10:11], s[60:61], s60, 31, v[46:47]
	s_and_b32 s31, s31, 0xe000
	s_waitcnt vmcnt(1)
	v_lshl_add_u32 v190, v10, 2, s84
	v_cndmask_b32_e64 v11, v194, v190, s[40:41]
	v_add_u32_e32 v14, s31, v61
	s_waitcnt lgkmcnt(0)
	s_barrier
	v_add_u32_e32 v27, v14, v55
	ds_read_b32 v18, v11
	v_add_u32_e32 v26, v14, v41
	ds_read_b128 v[14:17], v27
	v_cndmask_b32_e64 v11, v195, v190, s[42:43]
	ds_read_b32 v19, v11 offset:4
	v_cndmask_b32_e64 v11, v196, v190, s[44:45]
	ds_read_b32 v20, v11 offset:8
	v_cndmask_b32_e64 v11, v197, v190, s[46:47]
	ds_read_b32 v21, v11 offset:12
	v_cndmask_b32_e64 v11, v198, v190, s[48:49]
	ds_read_b32 v22, v11 offset:16
	v_cndmask_b32_e64 v11, v199, v190, s[50:51]
	ds_read_b32 v23, v11 offset:20
	v_cndmask_b32_e64 v11, v200, v190, s[52:53]
	v_cndmask_b32_e64 v10, v201, v190, s[54:55]
	ds_read_b32 v24, v11 offset:24
	ds_read_b32 v25, v10 offset:28
	ds_read_b128 v[10:13], v26
	s_waitcnt lgkmcnt(0)
	s_cmp_lg_u32 s32, 0
	s_cbranch_scc1 .Latt_vp1_pend
	s_waitcnt vmcnt(0)
	s_branch .Latt_vp1_done

; #define LAS __attribute__((address_space(3)))
; #define MFMA16(a, b, c) __builtin_amdgcn_mfma_f32_16x16x32_bf16((a), (b), (c), 0, 0, 0)
; __device__ __forceinline__ int att_fk(int key) { return ((key >> 3) & 3) + 4 * ((key >> 1) & 1); }
; __device__ __forceinline__ void attn_phase(const bf16_t* Q, const bf16_t* Kb, const bf16_t* VTa, const float* rpb, bf16_t* Y, LAS unsigned char* lds, int bx, int G, int tid, int wave, int lane) {
;     ...
; #pragma unroll
;             for (int ii = 0; ii < 4; ++ii) {
;                 const int i = 4 * hf + ii, dr = rs + i - r + 7;
;                 float bia[8];
; #pragma unroll
;                 for (int j = 0; j < 8; ++j) bia[j] = rl[((unsigned)(j - wlo) < (unsigned)wwd) ? dr * 31 + dci0 + j : 480];
; #pragma unroll
;                 for (int ta = 0; ta < 2; ++ta) {
;                     const int key = cs + 8 * (fr >> 2) + 4 * ta + (fr & 3), fk = att_fk(key);
;                     const LAS unsigned char* kp = KL + ((rs + i) & 7) * 8192 + key * 128;
;                     const bf16x8 kf0 = *(const LAS bf16x8*)(kp + ((fq ^ fk) << 4)), kf1 = *(const LAS bf16x8*)(kp + (((4 + fq) ^ fk) << 4));
;                     f32x4 a = {0.f, 0.f, 0.f, 0.f};
;                     a = MFMA16(kf0, qf0, a); a = MFMA16(kf1, qf1, a);
; #pragma unroll
;                     for (int idx = 0; idx < 4; ++idx) { a[idx] += bia[4 * ta + idx]; mx = fmaxf(mx, a[idx]); }
;                     s[ii][ta] = a;
;                 }
;             }
.Latt_vp1_done:
	v_mfma_f32_16x16x32_bf16 v[10:13], v[10:13], v[6:9], 0
	s_add_i32 s31, s30, s89
	s_sub_i32 s60, s31, s20
	s_lshl_b32 s31, s31, 13
	v_mfma_f32_16x16x32_bf16 v[14:17], v[14:17], v[2:5], v[10:13]
	s_and_b32 s31, s31, 0xe000
	s_nop 6
	v_add_f32_e32 v13, v18, v14
	v_add_f32_e32 v12, v19, v15
	v_max3_f32 v14, v13, s6, v12
	v_add_f32_e32 v11, v20, v16
	v_add_f32_e32 v10, v21, v17
	v_max3_f32 v28, v14, v11, v10
	ds_read_b128 v[14:17], v26 offset:512
	ds_read_b128 v[18:21], v27 offset:512
	s_waitcnt lgkmcnt(1)
	v_mfma_f32_16x16x32_bf16 v[14:17], v[14:17], v[6:9], 0
	s_waitcnt lgkmcnt(0)
	v_mfma_f32_16x16x32_bf16 v[18:21], v[18:21], v[2:5], v[14:17]
	s_nop 7
	v_add_f32_e32 v17, v22, v18
	v_add_f32_e32 v16, v23, v19
	v_max3_f32 v18, v28, v17, v16
	v_add_f32_e32 v15, v24, v20
	v_add_f32_e32 v14, v25, v21
	v_max3_f32 v26, v18, v15, v14
	v_mad_u64_u32 v[18:19], s[60:61], s60, 31, v[46:47]
	v_lshl_add_u32 v191, v18, 2, s84
	v_cndmask_b32_e64 v19, v194, v191, s[40:41]
	v_add_u32_e32 v22, s31, v61
	v_add_u32_e32 v63, v22, v55
	ds_read_b32 v27, v19
	v_add_u32_e32 v37, v22, v41
	ds_read_b128 v[22:25], v63
	v_cndmask_b32_e64 v19, v195, v191, s[42:43]
	ds_read_b32 v28, v19 offset:4
	v_cndmask_b32_e64 v19, v196, v191, s[44:45]
	ds_read_b32 v29, v19 offset:8
	v_cndmask_b32_e64 v19, v197, v191, s[46:47]
	ds_read_b32 v30, v19 offset:12
	v_cndmask_b32_e64 v19, v198, v191, s[48:49]
	ds_read_b32 v32, v19 offset:16
	v_cndmask_b32_e64 v19, v199, v191, s[50:51]
	ds_read_b32 v33, v19 offset:20
	v_cndmask_b32_e64 v19, v200, v191, s[52:53]
	v_cndmask_b32_e64 v18, v201, v191, s[54:55]
	ds_read_b32 v35, v19 offset:24
	ds_read_b32 v36, v18 offset:28
	ds_read_b128 v[18:21], v37
	s_waitcnt lgkmcnt(0)
	v_mfma_f32_16x16x32_bf16 v[18:21], v[18:21], v[6:9], 0
	s_add_i32 s31, s30, s90
	s_sub_i32 s60, s31, s20
	s_lshl_b32 s31, s31, 13
	v_mfma_f32_16x16x32_bf16 v[22:25], v[22:25], v[2:5], v[18:21]
	s_and_b32 s31, s31, 0xe000
	v_add_u32_e32 v73, s31, v61
	v_add_u32_e32 v75, v73, v41
	v_add_u32_e32 v73, v73, v55
	s_add_i32 s31, s30, s91
	s_nop 2
	v_add_f32_e32 v22, v27, v22
	v_add_f32_e32 v21, v28, v23
	v_max3_f32 v18, v26, v22, v21
	v_add_f32_e32 v20, v29, v24
	v_add_f32_e32 v19, v30, v25
	ds_read_b128 v[24:27], v37 offset:512
	ds_read_b128 v[92:95], v63 offset:512
	s_waitcnt lgkmcnt(1)
	v_mfma_f32_16x16x32_bf16 v[24:27], v[24:27], v[6:9], 0
	v_max3_f32 v18, v18, v20, v19
	s_waitcnt lgkmcnt(0)
	v_mfma_f32_16x16x32_bf16 v[24:27], v[92:95], v[2:5], v[24:27]
	ds_read_b128 v[92:95], v73
	s_nop 6
	v_add_f32_e32 v23, v32, v24
	v_add_f32_e32 v28, v33, v25
	v_mad_u64_u32 v[24:25], s[60:61], s60, 31, v[46:47]
	v_lshl_add_u32 v192, v24, 2, s84
	v_cndmask_b32_e64 v25, v194, v192, s[40:41]
	ds_read_b32 v32, v25
	v_cndmask_b32_e64 v25, v195, v192, s[42:43]
	ds_read_b32 v33, v25 offset:4
	v_cndmask_b32_e64 v25, v196, v192, s[44:45]
	v_add_f32_e32 v29, v35, v26
	ds_read_b32 v35, v25 offset:8
	v_cndmask_b32_e64 v25, v197, v192, s[46:47]
	v_add_f32_e32 v30, v36, v27
	ds_read_b32 v36, v25 offset:12
	v_cndmask_b32_e64 v25, v198, v192, s[48:49]
	ds_read_b32 v37, v25 offset:16
	v_cndmask_b32_e64 v25, v199, v192, s[50:51]
	ds_read_b32 v63, v25 offset:20
	v_cndmask_b32_e64 v25, v200, v192, s[52:53]
	v_cndmask_b32_e64 v24, v201, v192, s[54:55]
	ds_read_b32 v65, v25 offset:24
	ds_read_b32 v71, v24 offset:28
	ds_read_b128 v[24:27], v75
	s_waitcnt lgkmcnt(0)
	v_mfma_f32_16x16x32_bf16 v[24:27], v[24:27], v[6:9], 0
	s_sub_i32 s60, s31, s20
	s_lshl_b32 s31, s31, 13
	s_and_b32 s31, s31, 0xe000
	v_mfma_f32_16x16x32_bf16 v[24:27], v[92:95], v[2:5], v[24:27]
	v_add_u32_e32 v89, s31, v61
	v_add_u32_e32 v91, v89, v41
	v_add_u32_e32 v89, v89, v55
	v_max3_f32 v18, v18, v23, v28
	v_max3_f32 v18, v18, v29, v30
	s_nop 2
	v_add_f32_e32 v32, v32, v24
	v_add_f32_e32 v33, v33, v25
	v_add_f32_e32 v35, v35, v26
	v_add_f32_e32 v36, v36, v27
	ds_read_b128 v[24:27], v75 offset:512
	ds_read_b128 v[92:95], v73 offset:512
	s_waitcnt lgkmcnt(1)
	v_mfma_f32_16x16x32_bf16 v[24:27], v[24:27], v[6:9], 0
	v_max3_f32 v18, v18, v32, v33
	v_max3_f32 v18, v18, v35, v36
	s_waitcnt lgkmcnt(0)
	v_mfma_f32_16x16x32_bf16 v[24:27], v[92:95], v[2:5], v[24:27]
	ds_read_b128 v[92:95], v89
	s_nop 6
	v_add_f32_e32 v37, v37, v24
	v_add_f32_e32 v63, v63, v25
	v_mad_u64_u32 v[24:25], s[60:61], s60, 31, v[46:47]
	v_lshl_add_u32 v193, v24, 2, s84
	v_cndmask_b32_e64 v25, v194, v193, s[40:41]
	ds_read_b32 v73, v25
	v_cndmask_b32_e64 v25, v195, v193, s[42:43]
	ds_read_b32 v75, v25 offset:4
	v_cndmask_b32_e64 v25, v196, v193, s[44:45]
	ds_read_b32 v77, v25 offset:8
	v_cndmask_b32_e64 v25, v197, v193, s[46:47]
	ds_read_b32 v79, v25 offset:12
	v_cndmask_b32_e64 v25, v198, v193, s[48:49]
	ds_read_b32 v81, v25 offset:16
	v_cndmask_b32_e64 v25, v199, v193, s[50:51]
	ds_read_b32 v83, v25 offset:20
	v_cndmask_b32_e64 v25, v200, v193, s[52:53]
	v_cndmask_b32_e64 v24, v201, v193, s[54:55]
	v_add_f32_e32 v65, v65, v26
	v_add_f32_e32 v71, v71, v27
	ds_read_b32 v85, v25 offset:24
	ds_read_b32 v87, v24 offset:28
	ds_read_b128 v[24:27], v91
	s_waitcnt lgkmcnt(0)
	v_mfma_f32_16x16x32_bf16 v[24:27], v[24:27], v[6:9], 0
	v_max3_f32 v18, v18, v37, v63
	v_max3_f32 v18, v18, v65, v71
	v_mfma_f32_16x16x32_bf16 v[24:27], v[92:95], v[2:5], v[24:27]
	s_nop 7
	v_add_f32_e32 v73, v73, v24
	v_add_f32_e32 v75, v75, v25
	v_add_f32_e32 v77, v77, v26
	v_add_f32_e32 v79, v79, v27
	ds_read_b128 v[24:27], v91 offset:512
	ds_read_b128 v[92:95], v89 offset:512
	s_waitcnt lgkmcnt(1)
	v_mfma_f32_16x16x32_bf16 v[6:9], v[24:27], v[6:9], 0
	v_max3_f32 v18, v18, v73, v75
	v_max3_f32 v18, v18, v77, v79
	s_waitcnt lgkmcnt(0)
	s_waitcnt lgkmcnt(0)
	v_mfma_f32_16x16x32_bf16 v[2:5], v[92:95], v[2:5], v[6:9]
	s_barrier
; __device__ __forceinline__ float fast_exp2(float x) { return __builtin_amdgcn_exp2f(x); }
; __device__ __forceinline__ u32x4 pack8(f32x4 a, f32x4 b) { u32x4 w; w.x = cvt_pk_bf16(a[0], a[1]); w.y = cvt_pk_bf16(a[2], a[3]); w.z = cvt_pk_bf16(b[0], b[1]); w.w = cvt_pk_bf16(b[2], b[3]); return w; }
; #define SCHED_FENCE() __builtin_amdgcn_sched_barrier(0)
; #define ATT_BAR() do { asm volatile("s_waitcnt lgkmcnt(0)" ::: "memory"); __builtin_amdgcn_s_barrier(); asm volatile("" ::: "memory"); } while (0)
; __device__ __forceinline__ void attn_phase(const bf16_t* Q, const bf16_t* Kb, const bf16_t* VTa, const float* rpb, bf16_t* Y, LAS unsigned char* lds, int bx, int G, int tid, int wave, int lane) {
;     ...
;             mx = fmaxf(mx, __shfl_xor(mx, 16)); mx = fmaxf(mx, __shfl_xor(mx, 32));
;             float l = 0.f;
;             bf16x8 pb[4];
; #pragma unroll
;             for (int ii = 0; ii < 4; ++ii) {
;                 f32x4 p0, p1;
; #pragma unroll
;                 for (int idx = 0; idx < 4; ++idx) { p0[idx] = fast_exp2((s[ii][0][idx] - mx) * 1.4426950409f); p1[idx] = fast_exp2((s[ii][1][idx] - mx) * 1.4426950409f); }
;                 l += (p0[0] + p0[1]) + (p0[2] + p0[3]) + (p1[0] + p1[1]) + (p1[2] + p1[3]);
;                 const u32x4 pw = pack8(p0, p1); pb[ii] = __builtin_bit_cast(bf16x8, pw);
;             }
;             l += __shfl_xor(l, 16); l += __shfl_xor(l, 32);
;             SCHED_FENCE();
;             if (newrow) asm volatile("s_waitcnt vmcnt(3)" ::: "memory"); else if (has_next) asm volatile("s_waitcnt vmcnt(2)" ::: "memory"); else asm volatile("s_waitcnt vmcnt(0)" ::: "memory");
;             ATT_BAR();
	s_nop 6
	v_add_f32_e32 v24, v81, v2
	v_add_f32_e32 v25, v83, v3
	v_max3_f32 v2, v18, v24, v25
	v_add_f32_e32 v26, v85, v4
	v_add_f32_e32 v27, v87, v5
	v_max3_f32 v2, v2, v26, v27
	ds_bpermute_b32 v3, v31, v2
	s_waitcnt lgkmcnt(0)
	v_max_f32_e32 v3, v3, v3
	v_max_f32_e32 v2, v2, v3
	ds_bpermute_b32 v3, v34, v2
	s_waitcnt lgkmcnt(0)
	v_max_f32_e32 v3, v3, v3
	v_max_f32_e32 v18, v2, v3
	v_sub_f32_e32 v3, v17, v18
	v_sub_f32_e32 v4, v12, v18
	v_sub_f32_e32 v5, v16, v18
	v_mul_f32_e32 v3, 0x3fb8aa3b, v3
	v_mul_f32_e32 v4, 0x3fb8aa3b, v4
	v_mul_f32_e32 v5, 0x3fb8aa3b, v5
	v_sub_f32_e32 v2, v13, v18
	v_exp_f32_e32 v6, v3
	v_exp_f32_e32 v3, v4
	v_exp_f32_e32 v4, v5
	v_sub_f32_e32 v5, v11, v18
	v_sub_f32_e32 v8, v10, v18
	v_mul_f32_e32 v2, 0x3fb8aa3b, v2
	v_mul_f32_e32 v5, 0x3fb8aa3b, v5
	v_mul_f32_e32 v8, 0x3fb8aa3b, v8
	v_exp_f32_e32 v2, v2
	v_exp_f32_e32 v5, v5
	v_sub_f32_e32 v7, v15, v18
	v_exp_f32_e32 v8, v8
	v_sub_f32_e32 v9, v14, v18
	v_mul_f32_e32 v7, 0x3fb8aa3b, v7
	v_mul_f32_e32 v9, 0x3fb8aa3b, v9
	v_exp_f32_e32 v7, v7
	v_exp_f32_e32 v9, v9
	v_add_f32_e32 v10, v2, v3
	v_add_f32_e32 v11, v5, v8
	v_add_f32_e32 v10, v10, v11
	v_add_f32_e32 v11, v6, v4
	v_add_f32_e32 v10, v11, v10
	v_add_f32_e32 v11, v7, v9
	v_cvt_pk_bf16_f32 v2, v2, v3
	v_cvt_pk_bf16_f32 v3, v5, v8
	v_cvt_pk_bf16_f32 v4, v6, v4
	v_cvt_pk_bf16_f32 v5, v7, v9
	v_sub_f32_e32 v7, v23, v18
	v_mul_f32_e32 v7, 0x3fb8aa3b, v7
	v_add_f32_e32 v10, v11, v10
	v_sub_f32_e32 v6, v22, v18
	v_exp_f32_e32 v8, v7
	v_sub_f32_e32 v7, v21, v18
	v_sub_f32_e32 v11, v20, v18
	v_sub_f32_e32 v13, v19, v18
	v_mul_f32_e32 v6, 0x3fb8aa3b, v6
	v_mul_f32_e32 v7, 0x3fb8aa3b, v7
	v_sub_f32_e32 v9, v28, v18
	v_mul_f32_e32 v11, 0x3fb8aa3b, v11
	v_mul_f32_e32 v13, 0x3fb8aa3b, v13
	v_exp_f32_e32 v6, v6
	v_exp_f32_e32 v7, v7
	v_mul_f32_e32 v9, 0x3fb8aa3b, v9
	v_exp_f32_e32 v11, v11
	v_sub_f32_e32 v12, v29, v18
	v_exp_f32_e32 v13, v13
	v_sub_f32_e32 v14, v30, v18
	v_exp_f32_e32 v9, v9
	v_mul_f32_e32 v12, 0x3fb8aa3b, v12
	v_mul_f32_e32 v14, 0x3fb8aa3b, v14
	v_exp_f32_e32 v12, v12
	v_exp_f32_e32 v14, v14
	v_add_f32_e32 v15, v6, v7
	v_add_f32_e32 v16, v11, v13
	v_add_f32_e32 v15, v15, v16
	v_add_f32_e32 v16, v8, v9
	v_add_f32_e32 v15, v16, v15
	v_add_f32_e32 v16, v12, v14
	v_add_f32_e32 v10, 0, v10
	v_add_f32_e32 v15, v16, v15
	v_add_f32_e32 v10, v15, v10
	v_cvt_pk_bf16_f32 v6, v6, v7
	v_cvt_pk_bf16_f32 v7, v11, v13
	v_sub_f32_e32 v11, v32, v18
	v_sub_f32_e32 v13, v33, v18
	v_sub_f32_e32 v15, v35, v18
	v_sub_f32_e32 v17, v36, v18
	v_cvt_pk_bf16_f32 v8, v8, v9
	v_cvt_pk_bf16_f32 v9, v12, v14
	v_mul_f32_e32 v11, 0x3fb8aa3b, v11
	v_sub_f32_e32 v12, v37, v18
	v_mul_f32_e32 v13, 0x3fb8aa3b, v13
	v_sub_f32_e32 v14, v63, v18
	v_mul_f32_e32 v15, 0x3fb8aa3b, v15
	v_mul_f32_e32 v17, 0x3fb8aa3b, v17
	v_exp_f32_e32 v11, v11
	v_mul_f32_e32 v12, 0x3fb8aa3b, v12
	v_exp_f32_e32 v13, v13
	v_mul_f32_e32 v14, 0x3fb8aa3b, v14
	v_exp_f32_e32 v15, v15
	v_sub_f32_e32 v16, v65, v18
	v_exp_f32_e32 v17, v17
	v_sub_f32_e32 v19, v71, v18
	v_exp_f32_e32 v12, v12
	v_exp_f32_e32 v14, v14
	v_mul_f32_e32 v16, 0x3fb8aa3b, v16
	v_mul_f32_e32 v19, 0x3fb8aa3b, v19
	v_exp_f32_e32 v16, v16
	v_exp_f32_e32 v19, v19
	v_add_f32_e32 v20, v11, v13
	v_add_f32_e32 v21, v15, v17
	v_add_f32_e32 v20, v20, v21
	v_add_f32_e32 v21, v12, v14
	v_add_f32_e32 v20, v21, v20
	v_add_f32_e32 v21, v16, v19
	v_add_f32_e32 v20, v21, v20
	v_sub_f32_e32 v21, v24, v18
	v_mul_f32_e32 v21, 0x3fb8aa3b, v21
	v_add_f32_e32 v10, v20, v10
	v_sub_f32_e32 v20, v73, v18
	v_exp_f32_e32 v22, v21
	v_sub_f32_e32 v21, v75, v18
	v_sub_f32_e32 v23, v25, v18
	v_sub_f32_e32 v24, v77, v18
	v_sub_f32_e32 v25, v26, v18
	v_sub_f32_e32 v26, v79, v18
	v_mul_f32_e32 v20, 0x3fb8aa3b, v20
	v_mul_f32_e32 v21, 0x3fb8aa3b, v21
	v_mul_f32_e32 v24, 0x3fb8aa3b, v24
	v_mul_f32_e32 v26, 0x3fb8aa3b, v26
	v_exp_f32_e32 v20, v20
	v_exp_f32_e32 v21, v21
	v_mul_f32_e32 v23, 0x3fb8aa3b, v23
	v_exp_f32_e32 v24, v24
	v_exp_f32_e32 v26, v26
	v_sub_f32_e32 v27, v27, v18
	v_exp_f32_e32 v23, v23
	v_mul_f32_e32 v25, 0x3fb8aa3b, v25
	v_mul_f32_e32 v27, 0x3fb8aa3b, v27
	v_exp_f32_e32 v25, v25
	v_exp_f32_e32 v27, v27
	v_add_f32_e32 v28, v20, v21
	v_add_f32_e32 v29, v24, v26
	v_add_f32_e32 v28, v28, v29
	v_add_f32_e32 v29, v22, v23
	v_add_f32_e32 v28, v29, v28
	v_add_f32_e32 v29, v25, v27
	v_add_f32_e32 v28, v29, v28
	v_add_f32_e32 v28, v28, v10
	ds_bpermute_b32 v29, v31, v28
	v_cvt_pk_bf16_f32 v10, v11, v13
	v_cvt_pk_bf16_f32 v11, v15, v17
	v_cvt_pk_bf16_f32 v12, v12, v14
	v_cvt_pk_bf16_f32 v13, v16, v19
	s_waitcnt lgkmcnt(0)
	v_add_f32_e32 v14, v28, v29
	ds_bpermute_b32 v15, v34, v14
	v_cvt_pk_bf16_f32 v20, v20, v21
	v_cvt_pk_bf16_f32 v21, v24, v26
	v_cvt_pk_bf16_f32 v22, v22, v23
	v_cvt_pk_bf16_f32 v23, v25, v27
	s_waitcnt lgkmcnt(0)
	v_add_f32_e32 v19, v14, v15
	s_or_b32 s30, s30, s87
	s_lshl_b32 s30, s30, 13
	s_waitcnt vmcnt(0)
	s_and_b32 s31, s30, 0xe000
	s_waitcnt lgkmcnt(0)
	s_barrier
; #define LAS __attribute__((address_space(3)))
; __device__ __forceinline__ unsigned cvt_pk_bf16(float lo, float hi) { unsigned r; asm volatile("v_cvt_pk_bf16_f32 %0, %1, %2" : "=v"(r) : "v"(lo), "v"(hi)); return r; }
; #define MFMA16(a, b, c) __builtin_amdgcn_mfma_f32_16x16x32_bf16((a), (b), (c), 0, 0, 0)
; __device__ __forceinline__ int att_fv(int dh) { return (dh >> 1) & 7; }
; __device__ __forceinline__ void attn_phase(const bf16_t* Q, const bf16_t* Kb, const bf16_t* VTa, const float* rpb, bf16_t* Y, LAS unsigned char* lds, int bx, int G, int tid, int wave, int lane) {
;     ...
;             f32x4 o[4];
; #pragma unroll
;             for (int dt = 0; dt < 4; ++dt) o[dt] = (f32x4){0.f, 0.f, 0.f, 0.f};
; #pragma unroll
;             for (int ii = 0; ii < 4; ++ii) {
;                 const int i = 4 * hf + ii;
; #pragma unroll
;                 for (int dt = 0; dt < 4; ++dt) { const int dh = 16 * dt + fr;
;                     const bf16x8 vf = *(const LAS bf16x8*)(VL + ((rs + i) & 7) * 8192 + dh * 128 + ((((cs >> 3) + fq) ^ att_fv(dh)) << 4));
;                     o[dt] = MFMA16(vf, pb[ii], o[dt]); }
;             }
;             LAS float* ml = (LAS float*)(lds + 131072 + 2048) + (size_t)(g * 64 + lane) * 2;
;             LAS u32x2* ol = (LAS u32x2*)(lds + 131072 + 4096) + (size_t)(g * 64 + lane) * 4;
;             if (hf == 1) {
; #pragma unroll
;                 for (int dt = 0; dt < 4; ++dt) { u32x2 w; w.x = cvt_pk_bf16(o[dt][0], o[dt][1]); w.y = cvt_pk_bf16(o[dt][2], o[dt][3]); ol[dt] = w; }
;                 ml[0] = mx; ml[1] = l;
;             }
	v_add_u32_e32 v32, s31, v49
	s_add_i32 s31, s30, 0x2000
	s_and_b32 s31, s31, 0xe000
	v_add_u32_e32 v33, s31, v49
	s_add_i32 s31, s30, 0x4000
	s_and_b32 s31, s31, 0xe000
	v_add_u32_e32 v34, s31, v49
	s_addk_i32 s30, 0x6000
	s_and_b32 s30, s30, 0xe000
	v_add_u32_e32 v35, s30, v49
	s_and_b64 vcc, exec, s[58:59]
	ds_read_b128 v[108:111], v32
	ds_read_b128 v[112:115], v32 offset:2048
	ds_read_b128 v[116:119], v32 offset:4096
	ds_read_b128 v[120:123], v32 offset:6144
	ds_read_b128 v[124:127], v33
	ds_read_b128 v[128:131], v33 offset:2048
	ds_read_b128 v[132:135], v33 offset:4096
	ds_read_b128 v[136:139], v33 offset:6144
	ds_read_b128 v[140:143], v34
	ds_read_b128 v[144:147], v34 offset:2048
	ds_read_b128 v[148:151], v34 offset:4096
	ds_read_b128 v[152:155], v34 offset:6144
	ds_read_b128 v[174:177], v35
	ds_read_b128 v[178:181], v35 offset:2048
	ds_read_b128 v[182:185], v35 offset:4096
	ds_read_b128 v[186:189], v35 offset:6144
	s_waitcnt lgkmcnt(12)
	v_mfma_f32_16x16x32_bf16 v[14:17], v[108:111], v[2:5], 0
	v_mfma_f32_16x16x32_bf16 v[24:27], v[112:115], v[2:5], 0
	v_mfma_f32_16x16x32_bf16 v[28:31], v[116:119], v[2:5], 0
	v_mfma_f32_16x16x32_bf16 v[2:5], v[120:123], v[2:5], 0
	s_waitcnt lgkmcnt(8)
	v_mfma_f32_16x16x32_bf16 v[14:17], v[124:127], v[6:9], v[14:17]
	v_mfma_f32_16x16x32_bf16 v[24:27], v[128:131], v[6:9], v[24:27]
	v_mfma_f32_16x16x32_bf16 v[28:31], v[132:135], v[6:9], v[28:31]
	v_mfma_f32_16x16x32_bf16 v[2:5], v[136:139], v[6:9], v[2:5]
	s_waitcnt lgkmcnt(4)
	v_mfma_f32_16x16x32_bf16 v[14:17], v[140:143], v[10:13], v[14:17]
	v_mfma_f32_16x16x32_bf16 v[24:27], v[144:147], v[10:13], v[24:27]
	v_mfma_f32_16x16x32_bf16 v[28:31], v[148:151], v[10:13], v[28:31]
	v_mfma_f32_16x16x32_bf16 v[2:5], v[152:155], v[10:13], v[2:5]
	s_waitcnt lgkmcnt(0)
	v_mfma_f32_16x16x32_bf16 v[14:17], v[174:177], v[20:23], v[14:17]
	v_mfma_f32_16x16x32_bf16 v[10:13], v[178:181], v[20:23], v[24:27]
	v_mfma_f32_16x16x32_bf16 v[6:9], v[182:185], v[20:23], v[28:31]
	v_mfma_f32_16x16x32_bf16 v[2:5], v[186:189], v[20:23], v[2:5]
	s_nop 7
	v_add_u32_e32 v20, 0, v59
	v_add_u32_e32 v21, 0, v57
	v_add_u32_e32 v20, 0x21000, v20
	v_add_u32_e32 v21, 0x20800, v21
	s_cbranch_vccnz .LBB0_467
	v_cvt_pk_bf16_f32 v22, v14, v15
	v_cvt_pk_bf16_f32 v23, v16, v17
	ds_write_b64 v20, v[22:23]
	v_cvt_pk_bf16_f32 v22, v10, v11
	v_cvt_pk_bf16_f32 v23, v12, v13
	ds_write_b64 v20, v[22:23] offset:8
	v_cvt_pk_bf16_f32 v22, v6, v7
	v_cvt_pk_bf16_f32 v23, v8, v9
	ds_write_b64 v20, v[22:23] offset:16
	v_cvt_pk_bf16_f32 v22, v2, v3
	v_cvt_pk_bf16_f32 v23, v4, v5
	ds_write_b64 v20, v[22:23] offset:24
	ds_write_b64 v21, v[18:19]
